# G2 compute waves: VALU, LDS reads and SALU spread into the MFMA shadow (fine interleave), output stores deferred to the next step head
# baseline (speedup 1.0000x reference)
.Lg2c_loop:
	ds_read_b128 v[80:83], v238 offset:0
	ds_read_b128 v[84:87], v238 offset:4096
	ds_read_b128 v[88:91], v238 offset:8192
	ds_read_b128 v[92:95], v238 offset:12288
	ds_read_b128 v[96:99], v238 offset:16384
	ds_read_b128 v[100:103], v238 offset:20480
	ds_read_b128 v[104:107], v238 offset:24576
	ds_read_b128 v[108:111], v238 offset:28672
	ds_read_b128 v[112:115], v238 offset:1024
	ds_read_b128 v[116:119], v238 offset:5120
	ds_read_b128 v[120:123], v238 offset:9216
	ds_read_b128 v[124:127], v238 offset:13312
	ds_read_b128 v[128:131], v238 offset:17408
	ds_read_b128 v[132:135], v238 offset:21504
	ds_read_b128 v[136:139], v238 offset:25600
	ds_read_b128 v[140:143], v238 offset:29696
	s_cmp_eq_u32 s19, 0
	s_cbranch_scc1 .Lg2c_nost
	global_store_short v239, v78, s[28:29]
	global_store_short_d16_hi v239, v78, s[28:29] offset:2048
	global_store_short v240, v79, s[28:29]
	global_store_short_d16_hi v240, v79, s[28:29] offset:2048
	global_store_short v241, v193, s[28:29]
	global_store_short_d16_hi v241, v193, s[28:29] offset:2048
	global_store_short v242, v194, s[28:29]
	global_store_short_d16_hi v242, v194, s[28:29] offset:2048
	global_store_short v243, v195, s[28:29]
	global_store_short_d16_hi v243, v195, s[28:29] offset:2048
	global_store_short v246, v254, s[28:29]
	global_store_short_d16_hi v246, v254, s[28:29] offset:2048
	global_store_short v253, v255, s[28:29]
	global_store_short_d16_hi v253, v255, s[28:29] offset:2048
	global_store_short v248, v237, s[28:29]
	global_store_short_d16_hi v248, v237, s[28:29] offset:2048
	s_add_u32 s28, s28, 0x20000
	s_addc_u32 s29, s29, 0
.Lg2c_nost:
	v_cvt_pk_bf16_f32 v62, v4, v5
	v_cvt_pk_bf16_f32 v63, v6, v7
	v_cvt_pk_bf16_f32 v64, v8, v9
	v_cvt_pk_bf16_f32 v65, v10, v11
	s_waitcnt lgkmcnt(8)
	s_nop 0
	v_mfma_f32_16x16x32_bf16 v[176:179], v[80:83], v[62:65], 0
	ds_read_b128 v[144:147], v238 offset:2048
	ds_read_b128 v[148:151], v238 offset:6144
	ds_read_b128 v[152:155], v238 offset:10240
	v_mfma_f32_16x16x32_bf16 v[196:199], v[96:99], v[62:65], 0
	ds_read_b128 v[156:159], v238 offset:14336
	ds_read_b128 v[160:163], v238 offset:18432
	v_mfma_f32_16x16x32_bf16 v[180:183], v[84:87], v[62:65], 0
	ds_read_b128 v[164:167], v238 offset:22528
	ds_read_b128 v[168:171], v238 offset:26624
	ds_read_b128 v[172:175], v238 offset:30720
	v_mfma_f32_16x16x32_bf16 v[200:203], v[100:103], v[62:65], 0
	v_cvt_pk_bf16_f32 v66, v12, v13
	v_cvt_pk_bf16_f32 v67, v14, v15
	v_mfma_f32_16x16x32_bf16 v[184:187], v[88:91], v[62:65], 0
	v_cvt_pk_bf16_f32 v68, v16, v17
	v_cvt_pk_bf16_f32 v69, v18, v19
	v_cvt_pk_bf16_f32 v70, v20, v21
	v_mfma_f32_16x16x32_bf16 v[204:207], v[104:107], v[62:65], 0
	v_cvt_pk_bf16_f32 v71, v22, v23
	v_cvt_pk_bf16_f32 v72, v24, v25
	v_mfma_f32_16x16x32_bf16 v[188:191], v[92:95], v[62:65], 0
	v_cvt_pk_bf16_f32 v73, v26, v27
	v_cvt_pk_bf16_f32 v74, v28, v29
	v_cvt_pk_bf16_f32 v75, v30, v31
	v_mfma_f32_16x16x32_bf16 v[208:211], v[108:111], v[62:65], 0
	v_cvt_pk_bf16_f32 v76, v32, v33
	v_cvt_pk_bf16_f32 v77, v34, v35
	s_cmp_eq_u32 s19, 0
	s_cbranch_scc0 .Lg2c_w16
	s_waitcnt vmcnt(0)
.Lg2c_w16:
	s_waitcnt vmcnt(16)
	s_waitcnt lgkmcnt(8)
	v_mfma_f32_16x16x32_bf16 v[176:179], v[112:115], v[66:69], v[176:179]
	ds_read_b128 v[80:83], v238 offset:3072
	ds_read_b128 v[84:87], v238 offset:7168
	ds_read_b128 v[88:91], v238 offset:11264
	v_mfma_f32_16x16x32_bf16 v[196:199], v[128:131], v[66:69], v[196:199]
	ds_read_b128 v[92:95], v238 offset:15360
	ds_read_b128 v[96:99], v238 offset:19456
	ds_read_b128 v[100:103], v238 offset:23552
	v_mfma_f32_16x16x32_bf16 v[180:183], v[116:119], v[66:69], v[180:183]
	ds_read_b128 v[104:107], v238 offset:27648
	ds_read_b128 v[108:111], v238 offset:31744
	v_lshlrev_b32_e32 v212, 16, v50
	v_mfma_f32_16x16x32_bf16 v[200:203], v[132:135], v[66:69], v[200:203]
	v_and_b32_e32 v213, 0xffff0000, v50
	v_lshlrev_b32_e32 v214, 16, v51
	v_and_b32_e32 v215, 0xffff0000, v51
	v_mfma_f32_16x16x32_bf16 v[184:187], v[120:123], v[66:69], v[184:187]
	v_lshlrev_b32_e32 v216, 16, v52
	v_and_b32_e32 v217, 0xffff0000, v52
	v_lshlrev_b32_e32 v218, 16, v53
	v_mfma_f32_16x16x32_bf16 v[204:207], v[136:139], v[66:69], v[204:207]
	v_and_b32_e32 v219, 0xffff0000, v53
	v_lshlrev_b32_e32 v220, 16, v54
	v_and_b32_e32 v221, 0xffff0000, v54
	v_mfma_f32_16x16x32_bf16 v[188:191], v[124:127], v[66:69], v[188:191]
	v_lshlrev_b32_e32 v222, 16, v55
	v_and_b32_e32 v223, 0xffff0000, v55
	v_lshlrev_b32_e32 v224, 16, v56
	v_mfma_f32_16x16x32_bf16 v[208:211], v[140:143], v[66:69], v[208:211]
	v_and_b32_e32 v225, 0xffff0000, v56
	v_lshlrev_b32_e32 v226, 16, v57
	v_and_b32_e32 v227, 0xffff0000, v57
	s_waitcnt lgkmcnt(8)
	v_mfma_f32_16x16x32_bf16 v[176:179], v[144:147], v[70:73], v[176:179]
	v_pk_mul_f32 v[4:5], v[4:5], v[236:237] op_sel_hi:[1,0]
	v_pk_mul_f32 v[6:7], v[6:7], v[236:237] op_sel_hi:[1,0]
	v_mfma_f32_16x16x32_bf16 v[196:199], v[160:163], v[70:73], v[196:199]
	v_pk_mul_f32 v[8:9], v[8:9], v[236:237] op_sel_hi:[1,0]
	v_pk_mul_f32 v[10:11], v[10:11], v[236:237] op_sel_hi:[1,0]
	v_mfma_f32_16x16x32_bf16 v[180:183], v[148:151], v[70:73], v[180:183]
	v_pk_mul_f32 v[12:13], v[12:13], v[236:237] op_sel_hi:[1,0]
	v_pk_mul_f32 v[14:15], v[14:15], v[236:237] op_sel_hi:[1,0]
	v_mfma_f32_16x16x32_bf16 v[200:203], v[164:167], v[70:73], v[200:203]
	v_pk_mul_f32 v[16:17], v[16:17], v[236:237] op_sel_hi:[1,0]
	v_pk_mul_f32 v[18:19], v[18:19], v[236:237] op_sel_hi:[1,0]
	v_mfma_f32_16x16x32_bf16 v[184:187], v[152:155], v[70:73], v[184:187]
	v_pk_mul_f32 v[20:21], v[20:21], v[236:237] op_sel_hi:[1,0]
	v_pk_mul_f32 v[22:23], v[22:23], v[236:237] op_sel_hi:[1,0]
	v_mfma_f32_16x16x32_bf16 v[204:207], v[168:171], v[70:73], v[204:207]
	v_pk_mul_f32 v[24:25], v[24:25], v[236:237] op_sel_hi:[1,0]
	v_pk_mul_f32 v[26:27], v[26:27], v[236:237] op_sel_hi:[1,0]
	v_mfma_f32_16x16x32_bf16 v[188:191], v[156:159], v[70:73], v[188:191]
	v_pk_mul_f32 v[28:29], v[28:29], v[236:237] op_sel_hi:[1,0]
	v_pk_mul_f32 v[30:31], v[30:31], v[236:237] op_sel_hi:[1,0]
	v_mfma_f32_16x16x32_bf16 v[208:211], v[172:175], v[70:73], v[208:211]
	v_pk_mul_f32 v[32:33], v[32:33], v[236:237] op_sel_hi:[1,0]
	v_pk_mul_f32 v[34:35], v[34:35], v[236:237] op_sel_hi:[1,0]
	s_cmp_lt_u32 s19, 31
	s_cbranch_scc0 .Lg2c_noload
	global_load_dword v236, v1, s[36:37]
	global_load_dwordx2 v[50:51], v249, s[48:49] offset:0
	global_load_dwordx2 v[52:53], v249, s[48:49] offset:512
	global_load_dwordx2 v[54:55], v249, s[48:49] offset:1024
	global_load_dwordx2 v[56:57], v249, s[48:49] offset:1536
.Lg2c_noload:
	s_waitcnt lgkmcnt(0)
	s_barrier
	v_mfma_f32_16x16x32_bf16 v[176:179], v[80:83], v[74:77], v[176:179]
	ds_read_b128 v[112:115], v238 offset:32768
	ds_read_b128 v[116:119], v238 offset:34816
	ds_read_b128 v[120:123], v238 offset:36864
	ds_read_b128 v[124:127], v238 offset:38912
	v_mfma_f32_16x16x32_bf16 v[180:183], v[84:87], v[74:77], v[180:183]
	ds_read_b128 v[128:131], v238 offset:40960
	ds_read_b128 v[132:135], v238 offset:43008
	ds_read_b128 v[136:139], v238 offset:45056
	ds_read_b128 v[140:143], v238 offset:47104
	v_mfma_f32_16x16x32_bf16 v[184:187], v[88:91], v[74:77], v[184:187]
	ds_read_b128 v[144:147], v238 offset:33792
	ds_read_b128 v[148:151], v238 offset:35840
	ds_read_b128 v[152:155], v238 offset:37888
	ds_read_b128 v[156:159], v238 offset:39936
	v_mfma_f32_16x16x32_bf16 v[188:191], v[92:95], v[74:77], v[188:191]
	ds_read_b128 v[160:163], v238 offset:41984
	ds_read_b128 v[164:167], v238 offset:44032
	ds_read_b128 v[168:171], v238 offset:46080
	ds_read_b128 v[172:175], v238 offset:48128
	v_mfma_f32_16x16x32_bf16 v[196:199], v[96:99], v[74:77], v[196:199]
	v_sub_f32_e32 v212, v212, v176
	v_sub_f32_e32 v213, v213, v177
	v_sub_f32_e32 v214, v214, v178
	v_sub_f32_e32 v215, v215, v179
	v_mfma_f32_16x16x32_bf16 v[200:203], v[100:103], v[74:77], v[200:203]
	v_sub_f32_e32 v216, v216, v180
	v_sub_f32_e32 v217, v217, v181
	v_sub_f32_e32 v218, v218, v182
	v_sub_f32_e32 v219, v219, v183
	v_mfma_f32_16x16x32_bf16 v[204:207], v[104:107], v[74:77], v[204:207]
	v_sub_f32_e32 v220, v220, v184
	v_sub_f32_e32 v221, v221, v185
	v_sub_f32_e32 v222, v222, v186
	v_sub_f32_e32 v223, v223, v187
	v_mfma_f32_16x16x32_bf16 v[208:211], v[108:111], v[74:77], v[208:211]
	v_sub_f32_e32 v224, v224, v188
	v_sub_f32_e32 v225, v225, v189
	v_sub_f32_e32 v226, v226, v190
	v_sub_f32_e32 v227, v227, v191
	v_cvt_pk_bf16_f32 v228, v212, v213
	v_cvt_pk_bf16_f32 v229, v214, v215
	v_cvt_pk_bf16_f32 v230, v216, v217
	v_cvt_pk_bf16_f32 v231, v218, v219
	v_cvt_pk_bf16_f32 v232, v220, v221
	v_cvt_pk_bf16_f32 v233, v222, v223
	v_cvt_pk_bf16_f32 v234, v224, v225
	v_cvt_pk_bf16_f32 v235, v226, v227
	s_waitcnt lgkmcnt(8)
	s_nop 0
	v_mfma_f32_16x16x32_bf16 v[4:7], v[112:115], v[228:231], v[4:7]
	ds_read_b128 v[80:83], v238 offset:49152
	v_mfma_f32_16x16x32_bf16 v[8:11], v[116:119], v[228:231], v[8:11]
	ds_read_b128 v[84:87], v238 offset:51200
	v_mfma_f32_16x16x32_bf16 v[12:15], v[120:123], v[228:231], v[12:15]
	ds_read_b128 v[88:91], v238 offset:53248
	v_mfma_f32_16x16x32_bf16 v[16:19], v[124:127], v[228:231], v[16:19]
	ds_read_b128 v[92:95], v238 offset:55296
	v_mfma_f32_16x16x32_bf16 v[20:23], v[128:131], v[228:231], v[20:23]
	ds_read_b128 v[96:99], v238 offset:50176
	v_mfma_f32_16x16x32_bf16 v[24:27], v[132:135], v[228:231], v[24:27]
	ds_read_b128 v[100:103], v238 offset:52224
	v_mfma_f32_16x16x32_bf16 v[28:31], v[136:139], v[228:231], v[28:31]
	ds_read_b128 v[104:107], v238 offset:54272
	v_mfma_f32_16x16x32_bf16 v[32:35], v[140:143], v[228:231], v[32:35]
	ds_read_b128 v[108:111], v238 offset:56320
	s_waitcnt lgkmcnt(8)
	v_mfma_f32_16x16x32_bf16 v[4:7], v[144:147], v[232:235], v[4:7]
	v_mfma_f32_16x16x32_bf16 v[8:11], v[148:151], v[232:235], v[8:11]
	v_mfma_f32_16x16x32_bf16 v[12:15], v[152:155], v[232:235], v[12:15]
	v_mfma_f32_16x16x32_bf16 v[16:19], v[156:159], v[232:235], v[16:19]
	v_mfma_f32_16x16x32_bf16 v[20:23], v[160:163], v[232:235], v[20:23]
	v_mfma_f32_16x16x32_bf16 v[24:27], v[164:167], v[232:235], v[24:27]
	v_mfma_f32_16x16x32_bf16 v[28:31], v[168:171], v[232:235], v[28:31]
	v_mfma_f32_16x16x32_bf16 v[32:35], v[172:175], v[232:235], v[32:35]
	s_waitcnt lgkmcnt(0)
	v_mfma_f32_16x16x32_bf16 v[196:199], v[80:83], v[228:231], v[196:199]
	s_add_u32 s48, s48, 0x20000
	v_mfma_f32_16x16x32_bf16 v[200:203], v[84:87], v[228:231], v[200:203]
	s_addc_u32 s49, s49, 0
	v_mfma_f32_16x16x32_bf16 v[204:207], v[88:91], v[228:231], v[204:207]
	s_add_u32 s36, s36, 32
	v_mfma_f32_16x16x32_bf16 v[208:211], v[92:95], v[228:231], v[208:211]
	v_mfma_f32_16x16x32_bf16 v[196:199], v[96:99], v[232:235], v[196:199]
	s_addc_u32 s37, s37, 0
	v_mfma_f32_16x16x32_bf16 v[200:203], v[100:103], v[232:235], v[200:203]
	v_xor_b32_e32 v238, 0xe000, v238
	v_mfma_f32_16x16x32_bf16 v[204:207], v[104:107], v[232:235], v[204:207]
	s_add_i32 s19, s19, 1
	v_mfma_f32_16x16x32_bf16 v[208:211], v[108:111], v[232:235], v[208:211]
	s_nop 7
	v_cvt_pk_bf16_f32 v78, v196, v197
	v_cvt_pk_bf16_f32 v79, v198, v199
	v_cvt_pk_bf16_f32 v193, v200, v201
	v_cvt_pk_bf16_f32 v194, v202, v203
	v_cvt_pk_bf16_f32 v195, v204, v205
	v_cvt_pk_bf16_f32 v254, v206, v207
	v_cvt_pk_bf16_f32 v255, v208, v209
	v_cvt_pk_bf16_f32 v237, v210, v211
	s_cmp_lt_u32 s19, 32
	s_barrier
	s_cbranch_scc1 .Lg2c_loop
	global_store_short v239, v78, s[28:29]
	global_store_short_d16_hi v239, v78, s[28:29] offset:2048
	global_store_short v240, v79, s[28:29]
	global_store_short_d16_hi v240, v79, s[28:29] offset:2048
	global_store_short v241, v193, s[28:29]
	global_store_short_d16_hi v241, v193, s[28:29] offset:2048
	global_store_short v242, v194, s[28:29]
	global_store_short_d16_hi v242, v194, s[28:29] offset:2048
	global_store_short v243, v195, s[28:29]
	global_store_short_d16_hi v243, v195, s[28:29] offset:2048
	global_store_short v246, v254, s[28:29]
	global_store_short_d16_hi v246, v254, s[28:29] offset:2048
	global_store_short v253, v255, s[28:29]
	global_store_short_d16_hi v253, v255, s[28:29] offset:2048
	global_store_short v248, v237, s[28:29]
	global_store_short_d16_hi v248, v237, s[28:29] offset:2048
	s_add_u32 s28, s28, 0x20000
	s_addc_u32 s29, s29, 0
	s_branch .Lg2_exit
